# combined variant plus: the once-read f32 weight loads of the per-layer weight conversion marked nt
# speedup vs baseline: 1.0015x; 1.0015x over previous
; #define LAS __attribute__((address_space(3)))
; __device__ __forceinline__ void transpose_item(const float* W, int K, int N, bf16* WT, LAS float* scr, int item, int lane, const float* gk) {
;     const int nblk = N / 32, kb = item / nblk, nb = item % nblk, k0 = 64 * kb, n0 = 32 * nb;
;     float wv[32];
; #pragma unroll
;     for (int i = 0; i < 32; ++i) wv[i] = W[(size_t)(k0 + 2 * i + (lane >> 5)) * N + n0 + (lane & 31)];
;     if (gk) {
; #pragma unroll
;         for (int i = 0; i < 32; ++i) wv[i] *= gk[k0 + 2 * i + (lane >> 5)]; }
; #pragma unroll
;     for (int i = 0; i < 32; ++i) scr[(2 * i + (lane >> 5)) * 33 + (lane & 31)] = wv[i];
; __device__ __forceinline__ void ph_prologue(const Args& a, const Frame& F, int l) {
;     ...
;     for (int it = gw; it < NITEMS; it += NGW) {
;         int r = it;
;         if (r < I_IN) { transpose_item(a.in[I_WIN] + (size_t)l * DM * ZW, DM, ZW, (bf16*)(ws + WS_WIN), scr, r, lane, a.in[I_NMG] + (size_t)l * DM); continue; } r -= I_IN;
;         if (r < I_OUT) { transpose_item(a.in[I_WOUT] + (size_t)l * DM * DM, DM, DM, (bf16*)(ws + WS_WOUT), scr, r, lane, nullptr); continue; } r -= I_OUT;
;         if (r < I_UP) { transpose_item(a.in[I_WUP] + (size_t)l * DM * DFF, DM, DFF, (bf16*)(ws + WS_WUP), scr, r, lane, a.in[I_NLG] + (size_t)l * DM); continue; } r -= I_UP;
;         if (r < I_DN) { transpose_item(a.in[I_WDN] + (size_t)l * DFF * DM, DFF, DM, (bf16*)(ws + WS_WDN), scr, r, lane, nullptr); continue; } r -= I_DN;
;         transpose_item(a.in[I_WGLU] + (size_t)l * 512 * 512, 512, 512, (bf16*)(ws + WS_WGLU), scr, r, lane, nullptr);
.LBB0_16:
	s_cmpk_gt_i32 s51, 0x11ff
	s_mov_b64 s[36:37], -1
	s_cbranch_scc0 .LBB0_32
	s_cmpk_gt_u32 s51, 0x19ff
	s_cbranch_scc0 .LBB0_29
	s_cmpk_gt_u32 s51, 0x39ff
	s_cbranch_scc0 .LBB0_24
	s_cmpk_gt_u32 s51, 0x59ff
	s_cbranch_scc0 .LBB0_21
	s_and_b32 s5, s25, 0x3c0
	s_and_b32 s4, s0, 0x1e0
	v_or_b32_e32 v26, s5, v3
	s_lshl_b32 s82, s4, 2
	v_lshl_add_u64 v[24:25], v[14:15], 0, s[82:83]
	v_lshlrev_b32_e32 v190, 11, v26
	v_lshl_add_u64 v[24:25], v[24:25], 0, v[190:191]
	v_add_co_u32_e32 v26, vcc, 0x1000, v24
	s_mov_b32 s6, 0xa000
	s_nop 0
	v_addc_co_u32_e32 v27, vcc, 0, v25, vcc
	v_add_co_u32_e32 v28, vcc, 0x2000, v24
	s_lshl_b32 s82, s5, 1
	s_nop 0
	v_addc_co_u32_e32 v29, vcc, 0, v25, vcc
	v_add_co_u32_e32 v30, vcc, 0x3000, v24
	s_mov_b64 s[36:37], 0
	s_nop 0
	v_addc_co_u32_e32 v31, vcc, 0, v25, vcc
	v_add_co_u32_e32 v32, vcc, 0x4000, v24
	s_nop 1
	v_addc_co_u32_e32 v33, vcc, 0, v25, vcc
	v_add_co_u32_e32 v34, vcc, 0x5000, v24
	s_nop 1
	v_addc_co_u32_e32 v35, vcc, 0, v25, vcc
	v_add_co_u32_e32 v36, vcc, 0x6000, v24
	s_nop 1
	v_addc_co_u32_e32 v37, vcc, 0, v25, vcc
	v_add_co_u32_e32 v38, vcc, 0x7000, v24
	s_nop 1
	v_addc_co_u32_e32 v39, vcc, 0, v25, vcc
	global_load_dword v42, v[24:25], off nt
	global_load_dword v43, v[26:27], off nt
	global_load_dword v44, v[28:29], off nt
	global_load_dword v45, v[30:31], off nt
	global_load_dword v46, v[32:33], off nt
	global_load_dword v47, v[34:35], off nt
	global_load_dword v48, v[36:37], off nt
	global_load_dword v49, v[38:39], off nt
	v_add_co_u32_e32 v26, vcc, 0x8000, v24
	s_nop 1
	v_addc_co_u32_e32 v27, vcc, 0, v25, vcc
	v_add_co_u32_e32 v28, vcc, 0x9000, v24
	s_nop 1
	v_addc_co_u32_e32 v29, vcc, 0, v25, vcc
	v_add_co_u32_e32 v30, vcc, s6, v24
	s_mov_b32 s6, 0x12000
	s_nop 0
	v_addc_co_u32_e32 v31, vcc, 0, v25, vcc
	v_add_co_u32_e32 v32, vcc, 0xb000, v24
	s_nop 1
	v_addc_co_u32_e32 v33, vcc, 0, v25, vcc
	v_add_co_u32_e32 v34, vcc, 0xc000, v24
	s_nop 1
	v_addc_co_u32_e32 v35, vcc, 0, v25, vcc
	v_add_co_u32_e32 v36, vcc, 0xd000, v24
	s_nop 1
	v_addc_co_u32_e32 v37, vcc, 0, v25, vcc
	v_add_co_u32_e32 v38, vcc, 0xe000, v24
	s_nop 1
	v_addc_co_u32_e32 v39, vcc, 0, v25, vcc
	v_add_co_u32_e32 v40, vcc, 0xf000, v24
	s_nop 1
	v_addc_co_u32_e32 v41, vcc, 0, v25, vcc
	global_load_dword v50, v[26:27], off nt
	global_load_dword v51, v[28:29], off nt
	global_load_dword v52, v[30:31], off nt
	global_load_dword v53, v[32:33], off nt
	global_load_dword v54, v[34:35], off nt
	global_load_dword v55, v[36:37], off nt
	global_load_dword v56, v[38:39], off nt
	global_load_dword v57, v[40:41], off nt
	v_add_co_u32_e32 v26, vcc, 0x10000, v24
	s_nop 1
	v_addc_co_u32_e32 v27, vcc, 0, v25, vcc
	v_add_co_u32_e32 v28, vcc, 0x11000, v24
	s_nop 1
	v_addc_co_u32_e32 v29, vcc, 0, v25, vcc
	v_add_co_u32_e32 v30, vcc, s6, v24
	s_nop 1
	v_addc_co_u32_e32 v31, vcc, 0, v25, vcc
	v_add_co_u32_e32 v32, vcc, 0x13000, v24
	s_nop 1
	v_addc_co_u32_e32 v33, vcc, 0, v25, vcc
	v_add_co_u32_e32 v34, vcc, 0x14000, v24
	s_nop 1
	v_addc_co_u32_e32 v35, vcc, 0, v25, vcc
	v_add_co_u32_e32 v36, vcc, 0x15000, v24
	s_nop 1
	v_addc_co_u32_e32 v37, vcc, 0, v25, vcc
	v_add_co_u32_e32 v38, vcc, 0x16000, v24
	s_nop 1
	v_addc_co_u32_e32 v39, vcc, 0, v25, vcc
	v_add_co_u32_e32 v40, vcc, 0x17000, v24
	s_nop 1
	v_addc_co_u32_e32 v41, vcc, 0, v25, vcc
	global_load_dword v71, v[26:27], off nt
	global_load_dword v72, v[28:29], off nt
	global_load_dword v73, v[30:31], off nt
	global_load_dword v74, v[32:33], off nt
	global_load_dword v75, v[34:35], off nt
	global_load_dword v76, v[36:37], off nt
	global_load_dword v77, v[38:39], off nt
	s_nop 0
	global_load_dword v40, v[40:41], off nt
	v_add_co_u32_e32 v26, vcc, 0x18000, v24
	s_nop 1
	v_addc_co_u32_e32 v27, vcc, 0, v25, vcc
	v_add_co_u32_e32 v28, vcc, 0x19000, v24
	s_nop 1
	v_addc_co_u32_e32 v29, vcc, 0, v25, vcc
	v_add_co_u32_e32 v30, vcc, 0x1a000, v24
	s_nop 1
	v_addc_co_u32_e32 v31, vcc, 0, v25, vcc
	v_add_co_u32_e32 v32, vcc, 0x1b000, v24
	s_nop 1
	v_addc_co_u32_e32 v33, vcc, 0, v25, vcc
	v_add_co_u32_e32 v34, vcc, 0x1c000, v24
	s_nop 1
	v_addc_co_u32_e32 v35, vcc, 0, v25, vcc
	v_add_co_u32_e32 v36, vcc, 0x1d000, v24
	s_nop 1
	v_addc_co_u32_e32 v37, vcc, 0, v25, vcc
	v_add_co_u32_e32 v38, vcc, 0x1e000, v24
	s_nop 1
	v_addc_co_u32_e32 v39, vcc, 0, v25, vcc
	v_add_co_u32_e32 v24, vcc, 0x1f000, v24
	s_nop 1
	v_addc_co_u32_e32 v25, vcc, 0, v25, vcc
	global_load_dword v26, v[26:27], off nt
	s_nop 0
	global_load_dword v27, v[28:29], off nt
	s_nop 0
	global_load_dword v28, v[30:31], off nt
	global_load_dword v29, v[32:33], off nt
	s_nop 0
	global_load_dword v30, v[34:35], off nt
	global_load_dword v31, v[36:37], off nt
	global_load_dword v32, v[38:39], off nt
	s_nop 0
	global_load_dword v24, v[24:25], off nt
	s_waitcnt vmcnt(30)
	ds_write2_b32 v58, v42, v43 offset1:66
	s_waitcnt vmcnt(28)
	ds_write2_b32 v58, v44, v45 offset0:132 offset1:198
	s_waitcnt vmcnt(26)
	ds_write2_b32 v64, v46, v47 offset0:8 offset1:74
	s_waitcnt vmcnt(24)
	ds_write2_b32 v64, v48, v49 offset0:140 offset1:206
	s_waitcnt vmcnt(22)
	ds_write2_b32 v65, v50, v51 offset0:16 offset1:82
	s_waitcnt vmcnt(20)
	ds_write2_b32 v65, v52, v53 offset0:148 offset1:214
	s_waitcnt vmcnt(18)
	ds_write2_b32 v66, v54, v55 offset0:24 offset1:90
	s_waitcnt vmcnt(16)
	ds_write2_b32 v66, v56, v57 offset0:156 offset1:222
	s_waitcnt vmcnt(14)
	ds_write2_b32 v67, v71, v72 offset0:32 offset1:98
	s_waitcnt vmcnt(12)
	ds_write2_b32 v67, v73, v74 offset0:164 offset1:230
	s_waitcnt vmcnt(10)
	ds_write2_b32 v68, v75, v76 offset0:40 offset1:106
	s_waitcnt vmcnt(8)
	ds_write2_b32 v68, v77, v40 offset0:172 offset1:238
	s_waitcnt vmcnt(6)
	ds_write2_b32 v69, v26, v27 offset0:48 offset1:114
	s_waitcnt vmcnt(4)
; #define LAS __attribute__((address_space(3)))
; #define LDS_WAIT() asm volatile("s_waitcnt lgkmcnt(0)" ::: "memory")
; __device__ __forceinline__ unsigned pk2(float lo, float hi) { const f32x2 v = {lo, hi}; return __builtin_bit_cast(unsigned, __builtin_convertvector(v, bf16x2_t)); }
; __device__ __forceinline__ void transpose_item(const float* W, int K, int N, bf16* WT, LAS float* scr, int item, int lane, const float* gk) {
;     ...
;     for (int i = 0; i < 32; ++i) wv[i] = W[(size_t)(k0 + 2 * i + (lane >> 5)) * N + n0 + (lane & 31)];
;     ...
;     LDS_WAIT();
;     const int c = lane & 7;
; #pragma unroll
;     for (int j = 0; j < 4; ++j) { const int n = (lane >> 3) + 8 * j; const LAS float* s = scr + (8 * c) * 33 + n;
;         v4u o; o.x = pk2(s[0 * 33], s[1 * 33]); o.y = pk2(s[2 * 33], s[3 * 33]); o.z = pk2(s[4 * 33], s[5 * 33]); o.w = pk2(s[6 * 33], s[7 * 33]);
;         *(v4u*)(WT + (size_t)(n0 + n) * K + k0 + 8 * c) = o; }
;     LDS_WAIT();
; __device__ __forceinline__ void ph_prologue(const Args& a, const Frame& F, int l) {
;     ...
;         if (r < I_DN) { transpose_item(a.in[I_WDN] + (size_t)l * DFF * DM, DFF, DM, (bf16*)(ws + WS_WDN), scr, r, lane, nullptr); continue; } r -= I_DN;
	ds_write2_b32 v69, v28, v29 offset0:180 offset1:246
	s_waitcnt vmcnt(2)
	ds_write2_b32 v70, v30, v31 offset0:56 offset1:122
	s_waitcnt vmcnt(0)
	ds_write2_b32 v70, v32, v24 offset0:188 offset1:254
	s_waitcnt lgkmcnt(0)
	ds_read2_b32 v[28:29], v60 offset0:33 offset1:41
	ds_read2_b32 v[30:31], v60 offset1:8
	ds_read2_b32 v[32:33], v60 offset0:66 offset1:74
	ds_read2_b32 v[34:35], v60 offset0:99 offset1:107
	ds_read2_b32 v[36:37], v60 offset0:132 offset1:140
	ds_read2_b32 v[38:39], v60 offset0:165 offset1:173
	ds_read2_b32 v[40:41], v60 offset0:198 offset1:206
	ds_read2_b32 v[42:43], v60 offset0:231 offset1:239
	s_waitcnt lgkmcnt(6)
	v_cvt_pk_bf16_f32 v24, v30, v28
	v_or_b32_e32 v28, s4, v59
	v_lshl_add_u64 v[44:45], v[4:5], 0, s[82:83]
	v_lshlrev_b32_e32 v190, 10, v28
	s_waitcnt lgkmcnt(4)
	v_cvt_pk_bf16_f32 v25, v32, v34
	s_waitcnt lgkmcnt(2)
	v_cvt_pk_bf16_f32 v26, v36, v38
	s_waitcnt lgkmcnt(0)
	v_cvt_pk_bf16_f32 v27, v40, v42
	v_lshl_add_u64 v[46:47], v[44:45], 0, v[190:191]
	global_store_dwordx4 v[46:47], v[24:27], off
	v_or_b32_e32 v28, s4, v61
	v_lshlrev_b32_e32 v190, 10, v28
	v_cvt_pk_bf16_f32 v24, v31, v29
	v_cvt_pk_bf16_f32 v25, v33, v35
	v_cvt_pk_bf16_f32 v26, v37, v39
	v_cvt_pk_bf16_f32 v27, v41, v43
	ds_read2_b32 v[30:31], v60 offset0:49 offset1:57
	ds_read2_b32 v[32:33], v60 offset0:16 offset1:24
	ds_read2_b32 v[34:35], v60 offset0:82 offset1:90
	ds_read2_b32 v[36:37], v60 offset0:115 offset1:123
	ds_read2_b32 v[38:39], v60 offset0:148 offset1:156
	ds_read2_b32 v[40:41], v60 offset0:181 offset1:189
	ds_read2_b32 v[42:43], v60 offset0:214 offset1:222
	ds_read2_b32 v[46:47], v60 offset0:247 offset1:255
	v_lshl_add_u64 v[28:29], v[44:45], 0, v[190:191]
	global_store_dwordx4 v[28:29], v[24:27], off
	v_or_b32_e32 v28, s4, v62
	v_lshlrev_b32_e32 v190, 10, v28
	s_waitcnt lgkmcnt(6)
	v_cvt_pk_bf16_f32 v24, v32, v30
	s_waitcnt lgkmcnt(4)
	v_cvt_pk_bf16_f32 v25, v34, v36
	s_waitcnt lgkmcnt(2)
	v_cvt_pk_bf16_f32 v26, v38, v40
	s_waitcnt lgkmcnt(0)
	v_cvt_pk_bf16_f32 v27, v42, v46
	v_lshl_add_u64 v[28:29], v[44:45], 0, v[190:191]
	global_store_dwordx4 v[28:29], v[24:27], off
	v_or_b32_e32 v28, s4, v63
	v_lshlrev_b32_e32 v190, 10, v28
	v_cvt_pk_bf16_f32 v24, v33, v31
	v_cvt_pk_bf16_f32 v25, v35, v37
	v_cvt_pk_bf16_f32 v26, v39, v41
	v_cvt_pk_bf16_f32 v27, v43, v47
	v_lshl_add_u64 v[28:29], v[44:45], 0, v[190:191]
	global_store_dwordx4 v[28:29], v[24:27], off
	s_waitcnt lgkmcnt(0)
.LBB0_21:
	s_andn2_b64 vcc, exec, s[36:37]
	s_cbranch_vccnz .LBB0_23
	s_add_i32 s4, s51, 0xc600
	s_and_b32 s5, s4, 0xffc0
	s_and_b32 s4, s0, 0x7e0
	v_or_b32_e32 v26, s5, v3
	s_lshl_b32 s82, s4, 2
	v_lshl_add_u64 v[24:25], v[16:17], 0, s[82:83]
	v_lshlrev_b32_e32 v190, 13, v26
	v_lshl_add_u64 v[24:25], v[24:25], 0, v[190:191]
	v_add_co_u32_e32 v26, vcc, 0x4000, v24
	s_mov_b32 s6, 0x24000
	s_nop 0
	v_addc_co_u32_e32 v27, vcc, 0, v25, vcc
	v_add_co_u32_e32 v28, vcc, 0x8000, v24
	s_lshl_b32 s82, s5, 1
	s_nop 0
	v_addc_co_u32_e32 v29, vcc, 0, v25, vcc
	v_add_co_u32_e32 v30, vcc, 0xc000, v24
	s_nop 1
	v_addc_co_u32_e32 v31, vcc, 0, v25, vcc
	v_add_co_u32_e32 v32, vcc, 0x10000, v24
	s_nop 1
	v_addc_co_u32_e32 v33, vcc, 0, v25, vcc
	v_add_co_u32_e32 v34, vcc, 0x14000, v24
	s_nop 1
	v_addc_co_u32_e32 v35, vcc, 0, v25, vcc
	v_add_co_u32_e32 v36, vcc, 0x18000, v24
	s_nop 1
	v_addc_co_u32_e32 v37, vcc, 0, v25, vcc
	v_add_co_u32_e32 v38, vcc, 0x1c000, v24
	s_nop 1
	v_addc_co_u32_e32 v39, vcc, 0, v25, vcc
	global_load_dword v42, v[24:25], off nt
	global_load_dword v43, v[26:27], off nt
	global_load_dword v44, v[28:29], off nt
	global_load_dword v45, v[30:31], off nt
	global_load_dword v46, v[32:33], off nt
	global_load_dword v47, v[34:35], off nt
	global_load_dword v48, v[36:37], off nt
	global_load_dword v49, v[38:39], off nt
	v_add_co_u32_e32 v26, vcc, 0x20000, v24
	s_nop 1
	v_addc_co_u32_e32 v27, vcc, 0, v25, vcc
	v_add_co_u32_e32 v28, vcc, s6, v24
	s_nop 1
	v_addc_co_u32_e32 v29, vcc, 0, v25, vcc
	v_add_co_u32_e32 v30, vcc, 0x28000, v24
	s_nop 1
	v_addc_co_u32_e32 v31, vcc, 0, v25, vcc
	v_add_co_u32_e32 v32, vcc, 0x2c000, v24
	s_nop 1
	v_addc_co_u32_e32 v33, vcc, 0, v25, vcc
	v_add_co_u32_e32 v34, vcc, 0x30000, v24
	s_nop 1
	v_addc_co_u32_e32 v35, vcc, 0, v25, vcc
	v_add_co_u32_e32 v36, vcc, 0x34000, v24
	s_nop 1
	v_addc_co_u32_e32 v37, vcc, 0, v25, vcc
	v_add_co_u32_e32 v38, vcc, 0x38000, v24
	s_nop 1
	v_addc_co_u32_e32 v39, vcc, 0, v25, vcc
	v_add_co_u32_e32 v40, vcc, 0x3c000, v24
	s_nop 1
	v_addc_co_u32_e32 v41, vcc, 0, v25, vcc
	global_load_dword v50, v[26:27], off nt
	global_load_dword v51, v[28:29], off nt
	global_load_dword v52, v[30:31], off nt
	global_load_dword v53, v[32:33], off nt
	global_load_dword v54, v[34:35], off nt
	global_load_dword v55, v[36:37], off nt
	global_load_dword v56, v[38:39], off nt
	global_load_dword v57, v[40:41], off nt
	v_add_co_u32_e32 v26, vcc, 0x40000, v24
	s_nop 1
	v_addc_co_u32_e32 v27, vcc, 0, v25, vcc
	v_add_co_u32_e32 v28, vcc, 0x44000, v24
	s_nop 1
	v_addc_co_u32_e32 v29, vcc, 0, v25, vcc
	v_add_co_u32_e32 v30, vcc, 0x48000, v24
	s_nop 1
	v_addc_co_u32_e32 v31, vcc, 0, v25, vcc
	v_add_co_u32_e32 v32, vcc, 0x4c000, v24
	s_nop 1
	v_addc_co_u32_e32 v33, vcc, 0, v25, vcc
	v_add_co_u32_e32 v34, vcc, 0x50000, v24
	s_nop 1
	v_addc_co_u32_e32 v35, vcc, 0, v25, vcc
	v_add_co_u32_e32 v36, vcc, 0x54000, v24
	s_nop 1
	v_addc_co_u32_e32 v37, vcc, 0, v25, vcc
	v_add_co_u32_e32 v38, vcc, 0x58000, v24
	s_nop 1
	v_addc_co_u32_e32 v39, vcc, 0, v25, vcc
	v_add_co_u32_e32 v40, vcc, 0x5c000, v24
	s_nop 1
	v_addc_co_u32_e32 v41, vcc, 0, v25, vcc
	global_load_dword v71, v[26:27], off nt
	global_load_dword v72, v[28:29], off nt
	global_load_dword v73, v[30:31], off nt
	global_load_dword v74, v[32:33], off nt
	global_load_dword v75, v[34:35], off nt
	global_load_dword v76, v[36:37], off nt
	global_load_dword v77, v[38:39], off nt
	s_nop 0
	global_load_dword v40, v[40:41], off nt
	v_add_co_u32_e32 v26, vcc, 0x60000, v24
	s_nop 1
	v_addc_co_u32_e32 v27, vcc, 0, v25, vcc
	v_add_co_u32_e32 v28, vcc, 0x64000, v24
	s_nop 1
	v_addc_co_u32_e32 v29, vcc, 0, v25, vcc
	v_add_co_u32_e32 v30, vcc, 0x68000, v24
	s_nop 1
	v_addc_co_u32_e32 v31, vcc, 0, v25, vcc
	v_add_co_u32_e32 v32, vcc, 0x6c000, v24
	s_nop 1
	v_addc_co_u32_e32 v33, vcc, 0, v25, vcc
	v_add_co_u32_e32 v34, vcc, 0x70000, v24
	s_nop 1
	v_addc_co_u32_e32 v35, vcc, 0, v25, vcc
	v_add_co_u32_e32 v36, vcc, 0x74000, v24
	s_nop 1
	v_addc_co_u32_e32 v37, vcc, 0, v25, vcc
	v_add_co_u32_e32 v38, vcc, 0x78000, v24
	s_nop 1
	v_addc_co_u32_e32 v39, vcc, 0, v25, vcc
	v_add_co_u32_e32 v24, vcc, 0x7c000, v24
	s_nop 1
	v_addc_co_u32_e32 v25, vcc, 0, v25, vcc
	global_load_dword v26, v[26:27], off nt
	s_nop 0
	global_load_dword v27, v[28:29], off nt
	s_nop 0
	global_load_dword v28, v[30:31], off nt
	global_load_dword v29, v[32:33], off nt
	s_nop 0
	global_load_dword v30, v[34:35], off nt
	global_load_dword v31, v[36:37], off nt
	global_load_dword v32, v[38:39], off nt
	s_nop 0
	global_load_dword v24, v[24:25], off nt
	s_waitcnt vmcnt(30)
; #define LAS __attribute__((address_space(3)))
; #define LDS_WAIT() asm volatile("s_waitcnt lgkmcnt(0)" ::: "memory")
; __device__ __forceinline__ unsigned pk2(float lo, float hi) { const f32x2 v = {lo, hi}; return __builtin_bit_cast(unsigned, __builtin_convertvector(v, bf16x2_t)); }
; __device__ __forceinline__ void transpose_item(const float* W, int K, int N, bf16* WT, LAS float* scr, int item, int lane, const float* gk) {
;     ...
;     for (int i = 0; i < 32; ++i) scr[(2 * i + (lane >> 5)) * 33 + (lane & 31)] = wv[i];
;     LDS_WAIT();
;     const int c = lane & 7;
; #pragma unroll
;     for (int j = 0; j < 4; ++j) { const int n = (lane >> 3) + 8 * j; const LAS float* s = scr + (8 * c) * 33 + n;
;         v4u o; o.x = pk2(s[0 * 33], s[1 * 33]); o.y = pk2(s[2 * 33], s[3 * 33]); o.z = pk2(s[4 * 33], s[5 * 33]); o.w = pk2(s[6 * 33], s[7 * 33]);
;         *(v4u*)(WT + (size_t)(n0 + n) * K + k0 + 8 * c) = o; }
;     LDS_WAIT();
	ds_write2_b32 v58, v42, v43 offset1:66
	s_waitcnt vmcnt(28)
	ds_write2_b32 v58, v44, v45 offset0:132 offset1:198
	s_waitcnt vmcnt(26)
	ds_write2_b32 v64, v46, v47 offset0:8 offset1:74
	s_waitcnt vmcnt(24)
	ds_write2_b32 v64, v48, v49 offset0:140 offset1:206
	s_waitcnt vmcnt(22)
	ds_write2_b32 v65, v50, v51 offset0:16 offset1:82
	s_waitcnt vmcnt(20)
	ds_write2_b32 v65, v52, v53 offset0:148 offset1:214
	s_waitcnt vmcnt(18)
	ds_write2_b32 v66, v54, v55 offset0:24 offset1:90
	s_waitcnt vmcnt(16)
	ds_write2_b32 v66, v56, v57 offset0:156 offset1:222
	s_waitcnt vmcnt(14)
	ds_write2_b32 v67, v71, v72 offset0:32 offset1:98
	s_waitcnt vmcnt(12)
	ds_write2_b32 v67, v73, v74 offset0:164 offset1:230
	s_waitcnt vmcnt(10)
	ds_write2_b32 v68, v75, v76 offset0:40 offset1:106
	s_waitcnt vmcnt(8)
	ds_write2_b32 v68, v77, v40 offset0:172 offset1:238
	s_waitcnt vmcnt(6)
	ds_write2_b32 v69, v26, v27 offset0:48 offset1:114
	s_waitcnt vmcnt(4)
	ds_write2_b32 v69, v28, v29 offset0:180 offset1:246
	s_waitcnt vmcnt(2)
	ds_write2_b32 v70, v30, v31 offset0:56 offset1:122
	s_waitcnt vmcnt(0)
	ds_write2_b32 v70, v32, v24 offset0:188 offset1:254
	s_waitcnt lgkmcnt(0)
	ds_read2_b32 v[28:29], v60 offset0:33 offset1:41
	ds_read2_b32 v[30:31], v60 offset1:8
	ds_read2_b32 v[32:33], v60 offset0:66 offset1:74
	ds_read2_b32 v[34:35], v60 offset0:99 offset1:107
	ds_read2_b32 v[36:37], v60 offset0:132 offset1:140
	ds_read2_b32 v[38:39], v60 offset0:165 offset1:173
	ds_read2_b32 v[40:41], v60 offset0:198 offset1:206
	ds_read2_b32 v[42:43], v60 offset0:231 offset1:239
	s_waitcnt lgkmcnt(6)
	v_cvt_pk_bf16_f32 v24, v30, v28
	v_or_b32_e32 v28, s4, v59
	v_lshl_add_u64 v[44:45], v[6:7], 0, s[82:83]
	v_lshlrev_b32_e32 v190, 14, v28
	s_waitcnt lgkmcnt(4)
	v_cvt_pk_bf16_f32 v25, v32, v34
	s_waitcnt lgkmcnt(2)
	v_cvt_pk_bf16_f32 v26, v36, v38
	s_waitcnt lgkmcnt(0)
	v_cvt_pk_bf16_f32 v27, v40, v42
	v_lshl_add_u64 v[46:47], v[44:45], 0, v[190:191]
	global_store_dwordx4 v[46:47], v[24:27], off
	v_or_b32_e32 v28, s4, v61
	v_lshlrev_b32_e32 v190, 14, v28
	v_cvt_pk_bf16_f32 v24, v31, v29
	v_cvt_pk_bf16_f32 v25, v33, v35
	v_cvt_pk_bf16_f32 v26, v37, v39
	v_cvt_pk_bf16_f32 v27, v41, v43
	ds_read2_b32 v[30:31], v60 offset0:49 offset1:57
	ds_read2_b32 v[32:33], v60 offset0:16 offset1:24
	ds_read2_b32 v[34:35], v60 offset0:82 offset1:90
	ds_read2_b32 v[36:37], v60 offset0:115 offset1:123
	ds_read2_b32 v[38:39], v60 offset0:148 offset1:156
	ds_read2_b32 v[40:41], v60 offset0:181 offset1:189
	ds_read2_b32 v[42:43], v60 offset0:214 offset1:222
	ds_read2_b32 v[46:47], v60 offset0:247 offset1:255
	v_lshl_add_u64 v[28:29], v[44:45], 0, v[190:191]
	global_store_dwordx4 v[28:29], v[24:27], off
	v_or_b32_e32 v28, s4, v62
	v_lshlrev_b32_e32 v190, 14, v28
	s_waitcnt lgkmcnt(6)
	v_cvt_pk_bf16_f32 v24, v32, v30
	s_waitcnt lgkmcnt(4)
	v_cvt_pk_bf16_f32 v25, v34, v36
	s_waitcnt lgkmcnt(2)
	v_cvt_pk_bf16_f32 v26, v38, v40
	s_waitcnt lgkmcnt(0)
	v_cvt_pk_bf16_f32 v27, v42, v46
	v_lshl_add_u64 v[28:29], v[44:45], 0, v[190:191]
	global_store_dwordx4 v[28:29], v[24:27], off
	v_or_b32_e32 v28, s4, v63
	v_lshlrev_b32_e32 v190, 14, v28
	v_cvt_pk_bf16_f32 v24, v33, v31
	v_cvt_pk_bf16_f32 v25, v35, v37
	v_cvt_pk_bf16_f32 v26, v39, v41
	v_cvt_pk_bf16_f32 v27, v43, v47
	v_lshl_add_u64 v[28:29], v[44:45], 0, v[190:191]
	global_store_dwordx4 v[28:29], v[24:27], off
	s_waitcnt lgkmcnt(0)

; #define LAS __attribute__((address_space(3)))
; __device__ __forceinline__ void transpose_item(const float* W, int K, int N, bf16* WT, LAS float* scr, int item, int lane, const float* gk) {
;     const int nblk = N / 32, kb = item / nblk, nb = item % nblk, k0 = 64 * kb, n0 = 32 * nb;
;     float wv[32];
; #pragma unroll
;     for (int i = 0; i < 32; ++i) wv[i] = W[(size_t)(k0 + 2 * i + (lane >> 5)) * N + n0 + (lane & 31)];
; __device__ __forceinline__ void ph_prologue(const Args& a, const Frame& F, int l) {
;     ...
;         if (r < I_UP) { transpose_item(a.in[I_WUP] + (size_t)l * DM * DFF, DM, DFF, (bf16*)(ws + WS_WUP), scr, r, lane, a.in[I_NLG] + (size_t)l * DM); continue; } r -= I_UP;
.LBB0_24:
	s_andn2_b64 vcc, exec, s[36:37]
	s_cbranch_vccnz .LBB0_28
	s_add_i32 s4, s51, 0xe600
	s_bfe_u32 s4, s4, 0x80008
	s_lshl_b32 s5, s4, 6
	s_and_b32 s4, s0, 0x1fe0
	v_or_b32_e32 v56, s5, v3
	s_lshl_b32 s82, s4, 2
	v_lshlrev_b32_e32 v190, 15, v56
	v_lshl_add_u64 v[48:49], v[18:19], 0, s[82:83]
	v_or_b32_e32 v26, 0x10000, v190
	v_mov_b32_e32 v27, v191
	v_or_b32_e32 v28, 0x20000, v190
	v_mov_b32_e32 v29, v191
	v_or_b32_e32 v30, 0x30000, v190
	v_mov_b32_e32 v31, v191
	v_or_b32_e32 v32, 0x40000, v190
	v_mov_b32_e32 v33, v191
	v_or_b32_e32 v34, 0x50000, v190
	v_mov_b32_e32 v35, v191
	v_or_b32_e32 v36, 0x60000, v190
	v_mov_b32_e32 v37, v191
	v_or_b32_e32 v38, 0x70000, v190
	v_mov_b32_e32 v39, v191
	v_lshl_add_u64 v[24:25], v[48:49], 0, v[190:191]
	v_lshl_add_u64 v[26:27], v[48:49], 0, v[26:27]
	v_lshl_add_u64 v[28:29], v[48:49], 0, v[28:29]
	v_lshl_add_u64 v[30:31], v[48:49], 0, v[30:31]
	v_lshl_add_u64 v[32:33], v[48:49], 0, v[32:33]
	v_lshl_add_u64 v[34:35], v[48:49], 0, v[34:35]
	v_lshl_add_u64 v[36:37], v[48:49], 0, v[36:37]
	v_lshl_add_u64 v[38:39], v[48:49], 0, v[38:39]
	global_load_dword v24, v[24:25], off nt
	s_nop 0
	global_load_dword v25, v[26:27], off nt
	s_nop 0
	global_load_dword v26, v[28:29], off nt
	global_load_dword v27, v[30:31], off nt
	s_nop 0
	global_load_dword v28, v[32:33], off nt
	global_load_dword v29, v[34:35], off nt
	global_load_dword v30, v[36:37], off nt
	global_load_dword v31, v[38:39], off nt
	v_or_b32_e32 v32, 0x80000, v190
	v_mov_b32_e32 v33, v191
	v_or_b32_e32 v34, 0x90000, v190
	v_mov_b32_e32 v35, v191
	v_or_b32_e32 v36, 0xa0000, v190
	v_mov_b32_e32 v37, v191
	v_or_b32_e32 v38, 0xb0000, v190
	v_mov_b32_e32 v39, v191
	v_or_b32_e32 v40, 0xc0000, v190
	v_mov_b32_e32 v41, v191
	v_or_b32_e32 v42, 0xd0000, v190
	v_mov_b32_e32 v43, v191
	v_or_b32_e32 v44, 0xe0000, v190
	v_mov_b32_e32 v45, v191
	v_or_b32_e32 v46, 0xf0000, v190
	v_mov_b32_e32 v47, v191
	v_lshl_add_u64 v[32:33], v[48:49], 0, v[32:33]
	v_lshl_add_u64 v[34:35], v[48:49], 0, v[34:35]
	v_lshl_add_u64 v[36:37], v[48:49], 0, v[36:37]
	v_lshl_add_u64 v[38:39], v[48:49], 0, v[38:39]
	v_lshl_add_u64 v[40:41], v[48:49], 0, v[40:41]
	v_lshl_add_u64 v[42:43], v[48:49], 0, v[42:43]
	v_lshl_add_u64 v[44:45], v[48:49], 0, v[44:45]
	v_lshl_add_u64 v[46:47], v[48:49], 0, v[46:47]
	global_load_dword v32, v[32:33], off nt
	s_nop 0
	global_load_dword v33, v[34:35], off nt
	s_nop 0
	global_load_dword v34, v[36:37], off nt
	global_load_dword v35, v[38:39], off nt
	s_nop 0
	global_load_dword v36, v[40:41], off nt
	global_load_dword v37, v[42:43], off nt
	global_load_dword v38, v[44:45], off nt
	global_load_dword v39, v[46:47], off nt
	v_or_b32_e32 v40, 0x100000, v190
	v_mov_b32_e32 v41, v191
	v_or_b32_e32 v42, 0x110000, v190
	v_mov_b32_e32 v43, v191
	v_or_b32_e32 v44, 0x120000, v190
	v_mov_b32_e32 v45, v191
	v_or_b32_e32 v46, 0x130000, v190
	v_mov_b32_e32 v47, v191
	v_or_b32_e32 v50, 0x140000, v190
	v_mov_b32_e32 v51, v191
	v_or_b32_e32 v52, 0x150000, v190
	v_mov_b32_e32 v53, v191
	v_or_b32_e32 v54, 0x160000, v190
	v_mov_b32_e32 v55, v191
	v_lshl_add_u64 v[40:41], v[48:49], 0, v[40:41]
	v_lshl_add_u64 v[42:43], v[48:49], 0, v[42:43]
	v_lshl_add_u64 v[44:45], v[48:49], 0, v[44:45]
	v_lshl_add_u64 v[46:47], v[48:49], 0, v[46:47]
	v_lshl_add_u64 v[50:51], v[48:49], 0, v[50:51]
	v_lshl_add_u64 v[52:53], v[48:49], 0, v[52:53]
	v_lshl_add_u64 v[54:55], v[48:49], 0, v[54:55]
	v_or_b32_e32 v72, 0x170000, v190
	v_mov_b32_e32 v73, v191
	v_lshl_add_u64 v[72:73], v[48:49], 0, v[72:73]
	global_load_dword v40, v[40:41], off nt
	s_nop 0
	global_load_dword v41, v[42:43], off nt
	s_nop 0
	global_load_dword v42, v[44:45], off nt
	global_load_dword v43, v[46:47], off nt
	s_nop 0
	global_load_dword v44, v[50:51], off nt
	global_load_dword v45, v[52:53], off nt
	global_load_dword v46, v[54:55], off nt
	global_load_dword v47, v[72:73], off nt
	v_or_b32_e32 v50, 0x180000, v190
	v_mov_b32_e32 v51, v191
	v_or_b32_e32 v52, 0x190000, v190
	v_mov_b32_e32 v53, v191
	v_or_b32_e32 v54, 0x1a0000, v190
	v_mov_b32_e32 v55, v191
	v_lshl_add_u64 v[50:51], v[48:49], 0, v[50:51]
	v_lshl_add_u64 v[52:53], v[48:49], 0, v[52:53]
	v_lshl_add_u64 v[54:55], v[48:49], 0, v[54:55]
	v_or_b32_e32 v72, 0x1b0000, v190
	v_mov_b32_e32 v73, v191
	v_or_b32_e32 v74, 0x1c0000, v190
	v_mov_b32_e32 v75, v191
	v_or_b32_e32 v76, 0x1d0000, v190
	v_mov_b32_e32 v77, v191
	v_or_b32_e32 v78, 0x1e0000, v190
	v_mov_b32_e32 v79, v191
	v_or_b32_e32 v190, 0x1f0000, v190
	v_lshl_add_u64 v[72:73], v[48:49], 0, v[72:73]
	v_lshl_add_u64 v[74:75], v[48:49], 0, v[74:75]
	v_lshl_add_u64 v[76:77], v[48:49], 0, v[76:77]
	v_lshl_add_u64 v[78:79], v[48:49], 0, v[78:79]
	v_lshl_add_u64 v[80:81], v[48:49], 0, v[190:191]
	global_load_dword v48, v[50:51], off nt
	global_load_dword v49, v[52:53], off nt
	s_nop 0
	global_load_dword v50, v[54:55], off nt
	global_load_dword v51, v[72:73], off nt
	s_nop 0
	global_load_dword v54, v[74:75], off nt
	global_load_dword v55, v[76:77], off nt
	global_load_dword v52, v[78:79], off nt
	global_load_dword v53, v[80:81], off nt
	v_readlane_b32 s6, v249, 39
	v_readlane_b32 s7, v249, 40
	s_andn2_b64 vcc, exec, s[6:7]
	s_cbranch_vccnz .LBB0_27
; __device__ __forceinline__ void transpose_item(const float* W, int K, int N, bf16* WT, LAS float* scr, int item, int lane, const float* gk) {
;     ...
;     if (gk) {
; #pragma unroll
;         for (int i = 0; i < 32; ++i) wv[i] *= gk[k0 + 2 * i + (lane >> 5)]; }
	v_lshlrev_b32_e32 v71, 2, v56
	global_load_dword v56, v71, s[26:27] nt
	global_load_dword v57, v71, s[26:27] offset:8 nt
	global_load_dword v72, v71, s[26:27] offset:16 nt
	global_load_dword v73, v71, s[26:27] offset:24 nt
	global_load_dword v74, v71, s[26:27] offset:32 nt
	global_load_dword v75, v71, s[26:27] offset:40 nt
	global_load_dword v76, v71, s[26:27] offset:48 nt
	global_load_dword v77, v71, s[26:27] offset:56 nt
	global_load_dword v78, v71, s[26:27] offset:64 nt
	global_load_dword v79, v71, s[26:27] offset:72 nt
	global_load_dword v80, v71, s[26:27] offset:80 nt
	global_load_dword v81, v71, s[26:27] offset:88 nt
	global_load_dword v82, v71, s[26:27] offset:96 nt
	global_load_dword v83, v71, s[26:27] offset:104 nt
	global_load_dword v84, v71, s[26:27] offset:112 nt
	global_load_dword v85, v71, s[26:27] offset:120 nt
	global_load_dword v86, v71, s[26:27] offset:128 nt
	global_load_dword v87, v71, s[26:27] offset:136 nt
	global_load_dword v88, v71, s[26:27] offset:144 nt
	global_load_dword v89, v71, s[26:27] offset:152 nt
	global_load_dword v90, v71, s[26:27] offset:160 nt
	global_load_dword v91, v71, s[26:27] offset:168 nt
	global_load_dword v92, v71, s[26:27] offset:176 nt
	global_load_dword v93, v71, s[26:27] offset:184 nt
	global_load_dword v94, v71, s[26:27] offset:192 nt
	global_load_dword v95, v71, s[26:27] offset:200 nt
	global_load_dword v96, v71, s[26:27] offset:208 nt
	global_load_dword v97, v71, s[26:27] offset:216 nt
	global_load_dword v98, v71, s[26:27] offset:224 nt
	global_load_dword v99, v71, s[26:27] offset:232 nt
	global_load_dword v100, v71, s[26:27] offset:240 nt
	global_load_dword v101, v71, s[26:27] offset:248 nt
	s_waitcnt vmcnt(30)
	v_pk_mul_f32 v[24:25], v[24:25], v[56:57]
	s_waitcnt vmcnt(28)
	v_pk_mul_f32 v[26:27], v[26:27], v[72:73]
	s_waitcnt vmcnt(26)
	v_pk_mul_f32 v[28:29], v[28:29], v[74:75]
	s_waitcnt vmcnt(24)
	v_pk_mul_f32 v[30:31], v[30:31], v[76:77]
	s_waitcnt vmcnt(22)
	v_pk_mul_f32 v[32:33], v[32:33], v[78:79]
	s_waitcnt vmcnt(20)
	v_pk_mul_f32 v[34:35], v[34:35], v[80:81]
	s_waitcnt vmcnt(18)
	v_pk_mul_f32 v[36:37], v[36:37], v[82:83]
	s_waitcnt vmcnt(16)
	v_pk_mul_f32 v[38:39], v[38:39], v[84:85]
	s_waitcnt vmcnt(14)
	v_pk_mul_f32 v[40:41], v[40:41], v[86:87]
	s_waitcnt vmcnt(12)
	v_pk_mul_f32 v[42:43], v[42:43], v[88:89]
	s_waitcnt vmcnt(10)
	v_pk_mul_f32 v[44:45], v[44:45], v[90:91]
	s_waitcnt vmcnt(8)
	v_pk_mul_f32 v[46:47], v[46:47], v[92:93]
	s_waitcnt vmcnt(6)
	v_pk_mul_f32 v[48:49], v[48:49], v[94:95]
	s_waitcnt vmcnt(4)
	v_pk_mul_f32 v[50:51], v[50:51], v[96:97]
	s_waitcnt vmcnt(2)
	v_pk_mul_f32 v[54:55], v[54:55], v[98:99]
	s_waitcnt vmcnt(0)
	v_pk_mul_f32 v[52:53], v[52:53], v[100:101]

; #define LAS __attribute__((address_space(3)))
; __device__ __forceinline__ void transpose_item(const float* W, int K, int N, bf16* WT, LAS float* scr, int item, int lane, const float* gk) {
;     const int nblk = N / 32, kb = item / nblk, nb = item % nblk, k0 = 64 * kb, n0 = 32 * nb;
;     float wv[32];
; #pragma unroll
;     for (int i = 0; i < 32; ++i) wv[i] = W[(size_t)(k0 + 2 * i + (lane >> 5)) * N + n0 + (lane & 31)];
; __device__ __forceinline__ void ph_prologue(const Args& a, const Frame& F, int l) {
;     ...
;         if (r < I_OUT) { transpose_item(a.in[I_WOUT] + (size_t)l * DM * DM, DM, DM, (bf16*)(ws + WS_WOUT), scr, r, lane, nullptr); continue; } r -= I_OUT;
.LBB0_29:
	s_andn2_b64 vcc, exec, s[36:37]
	s_cbranch_vccnz .LBB0_31
	s_add_i32 s4, s51, 0xee00
	s_and_b32 s5, s4, 0xffc0
	s_and_b32 s4, s0, 0x7e0
	v_or_b32_e32 v26, s5, v3
	s_lshl_b32 s82, s4, 2
	v_lshl_add_u64 v[24:25], v[20:21], 0, s[82:83]
	v_lshlrev_b32_e32 v190, 13, v26
	v_lshl_add_u64 v[24:25], v[24:25], 0, v[190:191]
	v_add_co_u32_e32 v26, vcc, 0x4000, v24
	s_mov_b32 s6, 0x24000
	s_nop 0
	v_addc_co_u32_e32 v27, vcc, 0, v25, vcc
	v_add_co_u32_e32 v28, vcc, 0x8000, v24
	s_lshl_b32 s82, s5, 1
	s_nop 0
	v_addc_co_u32_e32 v29, vcc, 0, v25, vcc
	v_add_co_u32_e32 v30, vcc, 0xc000, v24
	s_nop 1
	v_addc_co_u32_e32 v31, vcc, 0, v25, vcc
	v_add_co_u32_e32 v32, vcc, 0x10000, v24
	s_nop 1
	v_addc_co_u32_e32 v33, vcc, 0, v25, vcc
	v_add_co_u32_e32 v34, vcc, 0x14000, v24
	s_nop 1
	v_addc_co_u32_e32 v35, vcc, 0, v25, vcc
	v_add_co_u32_e32 v36, vcc, 0x18000, v24
	s_nop 1
	v_addc_co_u32_e32 v37, vcc, 0, v25, vcc
	v_add_co_u32_e32 v38, vcc, 0x1c000, v24
	s_nop 1
	v_addc_co_u32_e32 v39, vcc, 0, v25, vcc
	global_load_dword v42, v[24:25], off nt
	global_load_dword v43, v[26:27], off nt
	global_load_dword v44, v[28:29], off nt
	global_load_dword v45, v[30:31], off nt
	global_load_dword v46, v[32:33], off nt
	global_load_dword v47, v[34:35], off nt
	global_load_dword v48, v[36:37], off nt
	global_load_dword v49, v[38:39], off nt
	v_add_co_u32_e32 v26, vcc, 0x20000, v24
	s_nop 1
	v_addc_co_u32_e32 v27, vcc, 0, v25, vcc
	v_add_co_u32_e32 v28, vcc, s6, v24
	s_nop 1
	v_addc_co_u32_e32 v29, vcc, 0, v25, vcc
	v_add_co_u32_e32 v30, vcc, 0x28000, v24
	s_nop 1
	v_addc_co_u32_e32 v31, vcc, 0, v25, vcc
	v_add_co_u32_e32 v32, vcc, 0x2c000, v24
	s_nop 1
	v_addc_co_u32_e32 v33, vcc, 0, v25, vcc
	v_add_co_u32_e32 v34, vcc, 0x30000, v24
	s_nop 1
	v_addc_co_u32_e32 v35, vcc, 0, v25, vcc
	v_add_co_u32_e32 v36, vcc, 0x34000, v24
	s_nop 1
	v_addc_co_u32_e32 v37, vcc, 0, v25, vcc
	v_add_co_u32_e32 v38, vcc, 0x38000, v24
	s_nop 1
	v_addc_co_u32_e32 v39, vcc, 0, v25, vcc
	v_add_co_u32_e32 v40, vcc, 0x3c000, v24
	s_nop 1
	v_addc_co_u32_e32 v41, vcc, 0, v25, vcc
	global_load_dword v50, v[26:27], off nt
	global_load_dword v51, v[28:29], off nt
	global_load_dword v52, v[30:31], off nt
	global_load_dword v53, v[32:33], off nt
	global_load_dword v54, v[34:35], off nt
	global_load_dword v55, v[36:37], off nt
	global_load_dword v56, v[38:39], off nt
	global_load_dword v57, v[40:41], off nt
	v_add_co_u32_e32 v26, vcc, 0x40000, v24
	s_nop 1
	v_addc_co_u32_e32 v27, vcc, 0, v25, vcc
	v_add_co_u32_e32 v28, vcc, 0x44000, v24
	s_nop 1
	v_addc_co_u32_e32 v29, vcc, 0, v25, vcc
	v_add_co_u32_e32 v30, vcc, 0x48000, v24
	s_nop 1
	v_addc_co_u32_e32 v31, vcc, 0, v25, vcc
	v_add_co_u32_e32 v32, vcc, 0x4c000, v24
	s_nop 1
	v_addc_co_u32_e32 v33, vcc, 0, v25, vcc
	v_add_co_u32_e32 v34, vcc, 0x50000, v24
	s_nop 1
	v_addc_co_u32_e32 v35, vcc, 0, v25, vcc
	v_add_co_u32_e32 v36, vcc, 0x54000, v24
	s_nop 1
	v_addc_co_u32_e32 v37, vcc, 0, v25, vcc
	v_add_co_u32_e32 v38, vcc, 0x58000, v24
	s_nop 1
	v_addc_co_u32_e32 v39, vcc, 0, v25, vcc
	v_add_co_u32_e32 v40, vcc, 0x5c000, v24
	s_nop 1
	v_addc_co_u32_e32 v41, vcc, 0, v25, vcc
	global_load_dword v71, v[26:27], off nt
	global_load_dword v72, v[28:29], off nt
	global_load_dword v73, v[30:31], off nt
	global_load_dword v74, v[32:33], off nt
	global_load_dword v75, v[34:35], off nt
	global_load_dword v76, v[36:37], off nt
	global_load_dword v77, v[38:39], off nt
	s_nop 0
	global_load_dword v40, v[40:41], off nt
	v_add_co_u32_e32 v26, vcc, 0x60000, v24
	s_nop 1
	v_addc_co_u32_e32 v27, vcc, 0, v25, vcc
	v_add_co_u32_e32 v28, vcc, 0x64000, v24
	s_nop 1
	v_addc_co_u32_e32 v29, vcc, 0, v25, vcc
	v_add_co_u32_e32 v30, vcc, 0x68000, v24
	s_nop 1
	v_addc_co_u32_e32 v31, vcc, 0, v25, vcc
	v_add_co_u32_e32 v32, vcc, 0x6c000, v24
	s_nop 1
	v_addc_co_u32_e32 v33, vcc, 0, v25, vcc
	v_add_co_u32_e32 v34, vcc, 0x70000, v24
	s_nop 1
	v_addc_co_u32_e32 v35, vcc, 0, v25, vcc
	v_add_co_u32_e32 v36, vcc, 0x74000, v24
	s_nop 1
	v_addc_co_u32_e32 v37, vcc, 0, v25, vcc
	v_add_co_u32_e32 v38, vcc, 0x78000, v24
	s_nop 1
	v_addc_co_u32_e32 v39, vcc, 0, v25, vcc
	v_add_co_u32_e32 v24, vcc, 0x7c000, v24
	s_nop 1
	v_addc_co_u32_e32 v25, vcc, 0, v25, vcc
	global_load_dword v26, v[26:27], off nt
	s_nop 0
	global_load_dword v27, v[28:29], off nt
	s_nop 0
	global_load_dword v28, v[30:31], off nt
	global_load_dword v29, v[32:33], off nt
	s_nop 0
	global_load_dword v30, v[34:35], off nt
	global_load_dword v31, v[36:37], off nt
	global_load_dword v32, v[38:39], off nt
	s_nop 0
	global_load_dword v24, v[24:25], off nt
	s_waitcnt vmcnt(30)
; #define LAS __attribute__((address_space(3)))
; #define LDS_WAIT() asm volatile("s_waitcnt lgkmcnt(0)" ::: "memory")
; __device__ __forceinline__ unsigned pk2(float lo, float hi) { const f32x2 v = {lo, hi}; return __builtin_bit_cast(unsigned, __builtin_convertvector(v, bf16x2_t)); }
; __device__ __forceinline__ void transpose_item(const float* W, int K, int N, bf16* WT, LAS float* scr, int item, int lane, const float* gk) {
;     ...
;     for (int i = 0; i < 32; ++i) scr[(2 * i + (lane >> 5)) * 33 + (lane & 31)] = wv[i];
;     LDS_WAIT();
;     const int c = lane & 7;
; #pragma unroll
;     for (int j = 0; j < 4; ++j) { const int n = (lane >> 3) + 8 * j; const LAS float* s = scr + (8 * c) * 33 + n;
;         v4u o; o.x = pk2(s[0 * 33], s[1 * 33]); o.y = pk2(s[2 * 33], s[3 * 33]); o.z = pk2(s[4 * 33], s[5 * 33]); o.w = pk2(s[6 * 33], s[7 * 33]);
;         *(v4u*)(WT + (size_t)(n0 + n) * K + k0 + 8 * c) = o; }
;     LDS_WAIT();
	ds_write2_b32 v58, v42, v43 offset1:66
	s_waitcnt vmcnt(28)
	ds_write2_b32 v58, v44, v45 offset0:132 offset1:198
	s_waitcnt vmcnt(26)
	ds_write2_b32 v64, v46, v47 offset0:8 offset1:74
	s_waitcnt vmcnt(24)
	ds_write2_b32 v64, v48, v49 offset0:140 offset1:206
	s_waitcnt vmcnt(22)
	ds_write2_b32 v65, v50, v51 offset0:16 offset1:82
	s_waitcnt vmcnt(20)
	ds_write2_b32 v65, v52, v53 offset0:148 offset1:214
	s_waitcnt vmcnt(18)
	ds_write2_b32 v66, v54, v55 offset0:24 offset1:90
	s_waitcnt vmcnt(16)
	ds_write2_b32 v66, v56, v57 offset0:156 offset1:222
	s_waitcnt vmcnt(14)
	ds_write2_b32 v67, v71, v72 offset0:32 offset1:98
	s_waitcnt vmcnt(12)
	ds_write2_b32 v67, v73, v74 offset0:164 offset1:230
	s_waitcnt vmcnt(10)
	ds_write2_b32 v68, v75, v76 offset0:40 offset1:106
	s_waitcnt vmcnt(8)
	ds_write2_b32 v68, v77, v40 offset0:172 offset1:238
	s_waitcnt vmcnt(6)
	ds_write2_b32 v69, v26, v27 offset0:48 offset1:114
	s_waitcnt vmcnt(4)
	ds_write2_b32 v69, v28, v29 offset0:180 offset1:246
	s_waitcnt vmcnt(2)
	ds_write2_b32 v70, v30, v31 offset0:56 offset1:122
	s_waitcnt vmcnt(0)
	ds_write2_b32 v70, v32, v24 offset0:188 offset1:254
	s_waitcnt lgkmcnt(0)
	ds_read2_b32 v[28:29], v60 offset0:33 offset1:41
	ds_read2_b32 v[30:31], v60 offset1:8
	ds_read2_b32 v[32:33], v60 offset0:66 offset1:74
	ds_read2_b32 v[34:35], v60 offset0:99 offset1:107
	ds_read2_b32 v[36:37], v60 offset0:132 offset1:140
	ds_read2_b32 v[38:39], v60 offset0:165 offset1:173
	ds_read2_b32 v[40:41], v60 offset0:198 offset1:206
	ds_read2_b32 v[42:43], v60 offset0:231 offset1:239
	s_waitcnt lgkmcnt(6)
	v_cvt_pk_bf16_f32 v24, v30, v28
	v_or_b32_e32 v28, s4, v59
	v_lshl_add_u64 v[44:45], v[10:11], 0, s[82:83]
	v_lshlrev_b32_e32 v190, 12, v28
	s_waitcnt lgkmcnt(4)
	v_cvt_pk_bf16_f32 v25, v32, v34
	s_waitcnt lgkmcnt(2)
	v_cvt_pk_bf16_f32 v26, v36, v38
	s_waitcnt lgkmcnt(0)
	v_cvt_pk_bf16_f32 v27, v40, v42
	v_lshl_add_u64 v[46:47], v[44:45], 0, v[190:191]
	global_store_dwordx4 v[46:47], v[24:27], off
	v_or_b32_e32 v28, s4, v61
	v_lshlrev_b32_e32 v190, 12, v28
	v_cvt_pk_bf16_f32 v24, v31, v29
	v_cvt_pk_bf16_f32 v25, v33, v35
	v_cvt_pk_bf16_f32 v26, v37, v39
	v_cvt_pk_bf16_f32 v27, v41, v43
	ds_read2_b32 v[30:31], v60 offset0:49 offset1:57
	ds_read2_b32 v[32:33], v60 offset0:16 offset1:24
	ds_read2_b32 v[34:35], v60 offset0:82 offset1:90
	ds_read2_b32 v[36:37], v60 offset0:115 offset1:123
	ds_read2_b32 v[38:39], v60 offset0:148 offset1:156
	ds_read2_b32 v[40:41], v60 offset0:181 offset1:189
	ds_read2_b32 v[42:43], v60 offset0:214 offset1:222
	ds_read2_b32 v[46:47], v60 offset0:247 offset1:255
	v_lshl_add_u64 v[28:29], v[44:45], 0, v[190:191]
	global_store_dwordx4 v[28:29], v[24:27], off
	v_or_b32_e32 v28, s4, v62
	v_lshlrev_b32_e32 v190, 12, v28
	s_waitcnt lgkmcnt(6)
	v_cvt_pk_bf16_f32 v24, v32, v30
	s_waitcnt lgkmcnt(4)
	v_cvt_pk_bf16_f32 v25, v34, v36
	s_waitcnt lgkmcnt(2)
	v_cvt_pk_bf16_f32 v26, v38, v40
	s_waitcnt lgkmcnt(0)
	v_cvt_pk_bf16_f32 v27, v42, v46
	v_lshl_add_u64 v[28:29], v[44:45], 0, v[190:191]
	global_store_dwordx4 v[28:29], v[24:27], off
	v_or_b32_e32 v28, s4, v63
	v_lshlrev_b32_e32 v190, 12, v28
	v_cvt_pk_bf16_f32 v24, v33, v31
	v_cvt_pk_bf16_f32 v25, v35, v37
	v_cvt_pk_bf16_f32 v26, v39, v41
	v_cvt_pk_bf16_f32 v27, v43, v47
	v_lshl_add_u64 v[28:29], v[44:45], 0, v[190:191]
	global_store_dwordx4 v[28:29], v[24:27], off
	s_waitcnt lgkmcnt(0)

; #define LAS __attribute__((address_space(3)))
; __device__ __forceinline__ void transpose_item(const float* W, int K, int N, bf16* WT, LAS float* scr, int item, int lane, const float* gk) {
;     const int nblk = N / 32, kb = item / nblk, nb = item % nblk, k0 = 64 * kb, n0 = 32 * nb;
;     float wv[32];
; #pragma unroll
;     for (int i = 0; i < 32; ++i) wv[i] = W[(size_t)(k0 + 2 * i + (lane >> 5)) * N + n0 + (lane & 31)];
; __device__ __forceinline__ void ph_prologue(const Args& a, const Frame& F, int l) {
;     ...
;         if (r < I_IN) { transpose_item(a.in[I_WIN] + (size_t)l * DM * ZW, DM, ZW, (bf16*)(ws + WS_WIN), scr, r, lane, a.in[I_NMG] + (size_t)l * DM); continue; } r -= I_IN;
.LBB0_32:
	s_andn2_b64 vcc, exec, s[36:37]
	s_cbranch_vccnz .LBB0_15
	s_mul_hi_i32 s4, s51, 0x38e38e39
	s_lshr_b32 s5, s4, 31
	s_ashr_i32 s4, s4, 5
	s_add_i32 s4, s4, s5
	s_lshl_b32 s54, s4, 6
	s_mulk_i32 s4, 0xee00
	s_add_i32 s46, s0, s4
	v_or_b32_e32 v56, s54, v3
	s_ashr_i32 s47, s46, 31
	v_lshl_add_u64 v[48:49], s[46:47], 2, v[22:23]
	s_movk_i32 s6, 0x4800
	v_or_b32_e32 v26, 2, v56
	v_or_b32_e32 v28, 4, v56
	v_or_b32_e32 v30, 6, v56
	v_or_b32_e32 v32, 8, v56
	v_or_b32_e32 v34, 10, v56
	v_or_b32_e32 v36, 12, v56
	v_or_b32_e32 v38, 14, v56
	v_mad_i64_i32 v[24:25], s[4:5], v56, s6, v[48:49]
	v_mad_i64_i32 v[26:27], s[4:5], v26, s6, v[48:49]
	v_mad_i64_i32 v[28:29], s[4:5], v28, s6, v[48:49]
	v_mad_i64_i32 v[30:31], s[4:5], v30, s6, v[48:49]
	v_mad_i64_i32 v[32:33], s[4:5], v32, s6, v[48:49]
	v_mad_i64_i32 v[34:35], s[4:5], v34, s6, v[48:49]
	v_mad_i64_i32 v[36:37], s[4:5], v36, s6, v[48:49]
	v_mad_i64_i32 v[38:39], s[4:5], v38, s6, v[48:49]
	global_load_dword v24, v[24:25], off nt
	s_nop 0
	global_load_dword v25, v[26:27], off nt
	s_nop 0
	global_load_dword v26, v[28:29], off nt
	global_load_dword v27, v[30:31], off nt
	s_nop 0
	global_load_dword v28, v[32:33], off nt
	global_load_dword v29, v[34:35], off nt
	global_load_dword v30, v[36:37], off nt
	global_load_dword v31, v[38:39], off nt
	v_or_b32_e32 v32, 16, v56
	v_or_b32_e32 v34, 18, v56
	v_or_b32_e32 v36, 20, v56
	v_or_b32_e32 v38, 22, v56
	v_or_b32_e32 v40, 24, v56
	v_or_b32_e32 v42, 26, v56
	v_or_b32_e32 v44, 28, v56
	v_or_b32_e32 v46, 30, v56
	v_mad_i64_i32 v[32:33], s[4:5], v32, s6, v[48:49]
	v_mad_i64_i32 v[34:35], s[4:5], v34, s6, v[48:49]
	v_mad_i64_i32 v[36:37], s[4:5], v36, s6, v[48:49]
	v_mad_i64_i32 v[38:39], s[4:5], v38, s6, v[48:49]
	v_mad_i64_i32 v[40:41], s[4:5], v40, s6, v[48:49]
	v_mad_i64_i32 v[42:43], s[4:5], v42, s6, v[48:49]
	v_mad_i64_i32 v[44:45], s[4:5], v44, s6, v[48:49]
	v_mad_i64_i32 v[46:47], s[4:5], v46, s6, v[48:49]
	global_load_dword v32, v[32:33], off nt
	s_nop 0
	global_load_dword v33, v[34:35], off nt
	s_nop 0
	global_load_dword v34, v[36:37], off nt
	global_load_dword v35, v[38:39], off nt
	s_nop 0
	global_load_dword v36, v[40:41], off nt
	global_load_dword v37, v[42:43], off nt
	global_load_dword v38, v[44:45], off nt
	global_load_dword v39, v[46:47], off nt
	v_or_b32_e32 v40, 32, v56
	v_or_b32_e32 v42, 34, v56
	v_or_b32_e32 v44, 36, v56
	v_or_b32_e32 v46, 38, v56
	v_or_b32_e32 v57, 46, v56
	v_mad_i64_i32 v[40:41], s[4:5], v40, s6, v[48:49]
	v_mad_i64_i32 v[42:43], s[4:5], v42, s6, v[48:49]
	v_mad_i64_i32 v[44:45], s[4:5], v44, s6, v[48:49]
	v_mad_i64_i32 v[46:47], s[4:5], v46, s6, v[48:49]
	v_or_b32_e32 v50, 40, v56
	v_or_b32_e32 v52, 42, v56
	v_or_b32_e32 v54, 44, v56
	v_mad_i64_i32 v[72:73], s[4:5], v57, s6, v[48:49]
	v_or_b32_e32 v57, 54, v56
	v_mad_i64_i32 v[50:51], s[4:5], v50, s6, v[48:49]
	v_mad_i64_i32 v[52:53], s[4:5], v52, s6, v[48:49]
	v_mad_i64_i32 v[54:55], s[4:5], v54, s6, v[48:49]
	global_load_dword v40, v[40:41], off nt
	s_nop 0
	global_load_dword v41, v[42:43], off nt
	s_nop 0
	global_load_dword v42, v[44:45], off nt
	global_load_dword v43, v[46:47], off nt
	s_nop 0
	global_load_dword v44, v[50:51], off nt
	global_load_dword v45, v[52:53], off nt
	global_load_dword v46, v[54:55], off nt
	global_load_dword v47, v[72:73], off nt
	v_mad_i64_i32 v[72:73], s[4:5], v57, s6, v[48:49]
	v_or_b32_e32 v57, 56, v56
	v_mad_i64_i32 v[74:75], s[4:5], v57, s6, v[48:49]
	v_or_b32_e32 v57, 58, v56
	v_or_b32_e32 v50, 48, v56
	v_or_b32_e32 v52, 50, v56
	v_or_b32_e32 v54, 52, v56
	v_mad_i64_i32 v[76:77], s[4:5], v57, s6, v[48:49]
	v_or_b32_e32 v57, 60, v56
	v_mad_i64_i32 v[50:51], s[4:5], v50, s6, v[48:49]
	v_mad_i64_i32 v[52:53], s[4:5], v52, s6, v[48:49]
	v_mad_i64_i32 v[54:55], s[4:5], v54, s6, v[48:49]
	v_mad_i64_i32 v[78:79], s[4:5], v57, s6, v[48:49]
	v_or_b32_e32 v57, 62, v56
	v_mad_i64_i32 v[80:81], s[4:5], v57, s6, v[48:49]
	global_load_dword v48, v[50:51], off nt
	global_load_dword v49, v[52:53], off nt
	s_nop 0
	global_load_dword v50, v[54:55], off nt
	global_load_dword v51, v[72:73], off nt
	s_nop 0
	global_load_dword v54, v[74:75], off nt
	global_load_dword v55, v[76:77], off nt
	global_load_dword v52, v[78:79], off nt
	global_load_dword v53, v[80:81], off nt
	v_readlane_b32 s4, v249, 41
	v_readlane_b32 s5, v249, 42
	s_andn2_b64 vcc, exec, s[4:5]
	s_cbranch_vccnz .LBB0_14
; __device__ __forceinline__ void transpose_item(const float* W, int K, int N, bf16* WT, LAS float* scr, int item, int lane, const float* gk) {
;     ...
;     if (gk) {
; #pragma unroll
;         for (int i = 0; i < 32; ++i) wv[i] *= gk[k0 + 2 * i + (lane >> 5)]; }
	v_ashrrev_i32_e32 v57, 31, v56
	v_lshl_add_u64 v[56:57], v[56:57], 2, s[38:39]
	global_load_dword v72, v[56:57], off nt
	global_load_dword v73, v[56:57], off offset:8 nt
	global_load_dword v74, v[56:57], off offset:16 nt
	global_load_dword v75, v[56:57], off offset:24 nt
	global_load_dword v76, v[56:57], off offset:32 nt
	global_load_dword v77, v[56:57], off offset:40 nt
	global_load_dword v78, v[56:57], off offset:48 nt
	global_load_dword v79, v[56:57], off offset:56 nt
	global_load_dword v80, v[56:57], off offset:64 nt
	global_load_dword v81, v[56:57], off offset:72 nt
	global_load_dword v82, v[56:57], off offset:80 nt
	global_load_dword v83, v[56:57], off offset:88 nt
	global_load_dword v84, v[56:57], off offset:96 nt
	global_load_dword v85, v[56:57], off offset:104 nt
	global_load_dword v86, v[56:57], off offset:112 nt
	global_load_dword v87, v[56:57], off offset:120 nt
	global_load_dword v88, v[56:57], off offset:128 nt
	global_load_dword v89, v[56:57], off offset:136 nt
	global_load_dword v90, v[56:57], off offset:144 nt
	global_load_dword v91, v[56:57], off offset:152 nt
	global_load_dword v92, v[56:57], off offset:160 nt
	global_load_dword v93, v[56:57], off offset:168 nt
	global_load_dword v94, v[56:57], off offset:176 nt
	global_load_dword v95, v[56:57], off offset:184 nt
	global_load_dword v96, v[56:57], off offset:192 nt
	global_load_dword v97, v[56:57], off offset:200 nt
	global_load_dword v98, v[56:57], off offset:208 nt
	global_load_dword v99, v[56:57], off offset:216 nt
	global_load_dword v100, v[56:57], off offset:224 nt
	global_load_dword v101, v[56:57], off offset:232 nt
	global_load_dword v102, v[56:57], off offset:240 nt
	global_load_dword v103, v[56:57], off offset:248 nt
	s_waitcnt vmcnt(30)
	v_pk_mul_f32 v[24:25], v[24:25], v[72:73]
	s_waitcnt vmcnt(28)
	v_pk_mul_f32 v[26:27], v[26:27], v[74:75]
	s_waitcnt vmcnt(26)
	v_pk_mul_f32 v[28:29], v[28:29], v[76:77]
	s_waitcnt vmcnt(24)
	v_pk_mul_f32 v[30:31], v[30:31], v[78:79]
	s_waitcnt vmcnt(22)
	v_pk_mul_f32 v[32:33], v[32:33], v[80:81]
	s_waitcnt vmcnt(20)
	v_pk_mul_f32 v[34:35], v[34:35], v[82:83]
	s_waitcnt vmcnt(18)
	v_pk_mul_f32 v[36:37], v[36:37], v[84:85]
	s_waitcnt vmcnt(16)
	v_pk_mul_f32 v[38:39], v[38:39], v[86:87]
	s_waitcnt vmcnt(14)
	v_pk_mul_f32 v[40:41], v[40:41], v[88:89]
	s_waitcnt vmcnt(12)
	v_pk_mul_f32 v[42:43], v[42:43], v[90:91]
	s_waitcnt vmcnt(10)
	v_pk_mul_f32 v[44:45], v[44:45], v[92:93]
	s_waitcnt vmcnt(8)
	v_pk_mul_f32 v[46:47], v[46:47], v[94:95]
	s_waitcnt vmcnt(6)
	v_pk_mul_f32 v[48:49], v[48:49], v[96:97]
	s_waitcnt vmcnt(4)
	v_pk_mul_f32 v[50:51], v[50:51], v[98:99]
	s_waitcnt vmcnt(2)
	v_pk_mul_f32 v[54:55], v[54:55], v[100:101]
	s_waitcnt vmcnt(0)
	v_pk_mul_f32 v[52:53], v[52:53], v[102:103]
	s_branch .LBB0_14
